# resid epilogue: K-loop drain and realigning barriers moved after the first epilogue loads are issued
# baseline (speedup 1.0000x reference)
.Lxr_t0:
	v_readlane_b32 s0, v254, 55
	s_mul_i32 s0, s49, s0
	s_add_i32 s0, s0, s68
	s_cmpk_gt_u32 s0, 0xff
	s_cbranch_scc1 .LBB0_894
	s_lshl_b32 s1, s0, 3
	s_and_b32 s1, s1, 56
	s_bfe_u32 s2, s0, 0x30003
	s_or_b32 s16, s1, s2
	s_lshr_b32 s2, s0, 6

.LBB0_896:
	v_readlane_b32 s0, v254, 38
	v_readlane_b32 s1, v254, 39
	s_xor_b64 s[18:19], s[4:5], -1
	s_lshl_b64 s[0:1], s[0:1], 2
	s_add_u32 s4, s24, s0
	s_addc_u32 s5, s25, s1
	v_readlane_b32 s0, v254, 47
	v_readlane_b32 s1, v254, 48
	s_and_b64 s[0:1], s[0:1], exec
	s_movk_i32 s0, 0x5000
	s_cselect_b32 s0, 0x2000, s0
	s_add_u32 s12, s4, s0
	s_addc_u32 s13, s5, 0
	v_ashrrev_i32_e32 v243, 31, v242
	v_lshl_add_u64 v[106:107], v[106:107], 2, s[12:13]
	v_lshl_add_u64 v[106:107], v[242:243], 2, v[106:107]
	flat_load_dwordx4 v[210:213], v[106:107] offset:16
	flat_load_dwordx4 v[214:217], v[106:107]
	flat_load_dwordx4 v[206:209], v[106:107] offset:528
	flat_load_dwordx2 v[244:245], v[106:107] offset:512
	flat_load_dwordx2 v[250:251], v[106:107] offset:520
	s_waitcnt vmcnt(0)
	s_cmpk_gt_u32 s31, 0xff
	s_cbranch_scc1 .Lrs_nobar
	s_barrier
.Lrs_nobar:
	s_barrier
	v_cndmask_b32_e64 v0, 0, 1, s[18:19]
	s_movk_i32 s0, 0x1fef
	v_cmp_lt_i32_e64 s[4:5], s0, v249
	v_cmp_ne_u32_e64 s[0:1], 1, v0
	s_andn2_b64 vcc, exec, s[18:19]
	s_waitcnt vmcnt(0) lgkmcnt(0)
	v_mov_b64_e32 v[186:187], v[210:211]
	v_mov_b64_e32 v[194:195], v[214:215]
	v_mov_b64_e32 v[188:189], v[212:213]
	v_mov_b64_e32 v[196:197], v[216:217]
	s_cbranch_vccnz .LBB0_898
	s_add_i32 s15, s14, 0xffffe010
	s_lshr_b32 s15, s15, 10
	s_mulk_i32 s15, 0x1800
	s_addk_i32 s15, 0x1800
	v_mov_b32_e32 v0, s15
	v_cndmask_b32_e64 v0, 0, v0, s[4:5]
	v_lshl_add_u64 v[106:107], v[0:1], 2, s[12:13]
	v_lshl_add_u64 v[106:107], v[242:243], 2, v[106:107]
	flat_load_dwordx4 v[194:197], v[106:107]
	flat_load_dwordx4 v[186:189], v[106:107] offset:16
